# v95 + tightened permlane exchange + alpha subtraction moved into the rare rescale block where safe
# speedup vs baseline: 1.0006x; 1.0006x over previous
.Lrs_0:
	v_max3_f32 v0, v80, s18, v81
	v_max3_f32 v0, v0, v82, v83
	v_max3_f32 v0, v0, v84, v85
	v_max3_f32 v0, v0, v86, v87
	v_max3_f32 v0, v0, v88, v89
	v_max3_f32 v0, v0, v90, v91
	v_max3_f32 v0, v0, v92, v93
	v_max3_f32 v10, v0, v94, v95
	v_max3_f32 v255, v0, v94, v95
	s_waitcnt lgkmcnt(0)
	s_nop 0
	v_permlane32_swap_b32_e32 v10, v255
	v_max3_f32 v14, v235, v10, v255
	v_sub_f32_e32 v255, v14, v235
	v_cmp_lt_f32_e64 s[98:99], 4.0, v255
	s_nop 1
	v_cndmask_b32_e64 v14, v235, v14, s[98:99]
	v_sub_f32_e32 v0, v80, v14
	v_exp_f32_e32 v11, v0
	v_sub_f32_e32 v12, v81, v14
	v_exp_f32_e32 v12, v12
	v_sub_f32_e32 v13, v82, v14
	v_exp_f32_e32 v13, v13
	v_sub_f32_e32 v80, v83, v14
	v_exp_f32_e32 v81, v80
	v_sub_f32_e32 v80, v84, v14
	v_add_f32_e32 v0, 0, v11
	v_exp_f32_e32 v82, v80
	v_sub_f32_e32 v80, v85, v14
	v_add_f32_e32 v0, v12, v0
	v_exp_f32_e32 v83, v80
	v_sub_f32_e32 v80, v86, v14
	v_add_f32_e32 v0, v13, v0
	v_exp_f32_e32 v84, v80
	v_sub_f32_e32 v80, v87, v14
	v_add_f32_e32 v0, v81, v0
	v_exp_f32_e32 v85, v80
	v_sub_f32_e32 v80, v88, v14
	v_add_f32_e32 v0, v82, v0
	v_exp_f32_e32 v86, v80
	v_sub_f32_e32 v80, v89, v14
	v_add_f32_e32 v0, v83, v0
	v_exp_f32_e32 v87, v80
	v_sub_f32_e32 v80, v90, v14
	v_add_f32_e32 v0, v84, v0
	v_exp_f32_e32 v88, v80
	v_sub_f32_e32 v80, v91, v14
	v_add_f32_e32 v0, v85, v0
	v_exp_f32_e32 v89, v80
	v_sub_f32_e32 v80, v92, v14
	v_add_f32_e32 v0, v86, v0
	v_exp_f32_e32 v90, v80
	v_sub_f32_e32 v80, v93, v14
	v_add_f32_e32 v0, v87, v0
	v_exp_f32_e32 v91, v80
	v_sub_f32_e32 v80, v94, v14
	v_add_f32_e32 v0, v88, v0
	v_exp_f32_e32 v92, v80
	v_sub_f32_e32 v80, v95, v14
	v_add_f32_e32 v0, v89, v0
	v_exp_f32_e32 v93, v80
	v_add_f32_e32 v0, v90, v0
	v_add_f32_e32 v0, v91, v0
	v_add_f32_e32 v0, v92, v0
	v_add_f32_e32 v0, v93, v0
	s_mov_b64 vcc, s[98:99]
	s_cbranch_vccz .Lrse_1
	v_sub_f32_e32 v10, v235, v14
	v_exp_f32_e32 v10, v10
	s_nop 0
	v_fmac_f32_e32 v0, v15, v10
	v_mul_f32_e32 v46, v10, v46
	v_mul_f32_e32 v47, v10, v47
	v_mul_f32_e32 v44, v10, v44
	v_mul_f32_e32 v45, v10, v45
	v_mul_f32_e32 v42, v10, v42
	v_mul_f32_e32 v43, v10, v43
	v_mul_f32_e32 v40, v10, v40
	v_mul_f32_e32 v41, v10, v41
	v_mul_f32_e32 v38, v10, v38
	v_mul_f32_e32 v39, v10, v39
	v_mul_f32_e32 v36, v10, v36
	v_mul_f32_e32 v37, v10, v37
	v_mul_f32_e32 v34, v10, v34
	v_mul_f32_e32 v35, v10, v35
	v_mul_f32_e32 v32, v10, v32
	v_mul_f32_e32 v33, v10, v33
	v_mul_f32_e32 v30, v10, v30
	v_mul_f32_e32 v31, v10, v31
	v_mul_f32_e32 v28, v10, v28
	v_mul_f32_e32 v29, v10, v29
	v_mul_f32_e32 v26, v10, v26
	v_mul_f32_e32 v27, v10, v27
	v_mul_f32_e32 v24, v10, v24
	v_mul_f32_e32 v25, v10, v25
	v_mul_f32_e32 v22, v10, v22
	v_mul_f32_e32 v23, v10, v23
	v_mul_f32_e32 v20, v10, v20
	v_mul_f32_e32 v21, v10, v21
	v_mul_f32_e32 v18, v10, v18
	v_mul_f32_e32 v19, v10, v19
	v_mul_f32_e32 v16, v10, v16
	v_mul_f32_e32 v17, v10, v17
	s_branch .Lrs_1

.LBB0_347:
	v_add_f32_e32 v11, 0, v235
	v_add_f32_e32 v11, v236, v11
	v_add_f32_e32 v11, v237, v11
	v_add_f32_e32 v11, v238, v11
	v_add_f32_e32 v11, v239, v11
	v_add_f32_e32 v11, v240, v11
	v_add_f32_e32 v11, v241, v11
	v_add_f32_e32 v11, v242, v11
	v_add_f32_e32 v11, v243, v11
	v_add_f32_e32 v11, v244, v11
	v_add_f32_e32 v11, v245, v11
	v_add_f32_e32 v11, v246, v11
	v_add_f32_e32 v11, v247, v11
	v_add_f32_e32 v11, v248, v11
	v_add_f32_e32 v11, v249, v11
	v_add_f32_e32 v160, v250, v11
	s_mov_b64 vcc, s[98:99]
	s_cbranch_vccz .Lrse_2
	v_sub_f32_e32 v10, v234, v233
	v_exp_f32_e32 v10, v10
	s_nop 0
	v_fmac_f32_e32 v160, v232, v10
	v_mul_f32_e32 v78, v10, v78
	v_mul_f32_e32 v79, v10, v79
	v_mul_f32_e32 v76, v10, v76
	v_mul_f32_e32 v77, v10, v77
	v_mul_f32_e32 v74, v10, v74
	v_mul_f32_e32 v75, v10, v75
	v_mul_f32_e32 v72, v10, v72
	v_mul_f32_e32 v73, v10, v73
	v_mul_f32_e32 v70, v10, v70
	v_mul_f32_e32 v71, v10, v71
	v_mul_f32_e32 v68, v10, v68
	v_mul_f32_e32 v69, v10, v69
	v_mul_f32_e32 v66, v10, v66
	v_mul_f32_e32 v67, v10, v67
	v_mul_f32_e32 v64, v10, v64
	v_mul_f32_e32 v65, v10, v65
	v_mul_f32_e32 v62, v10, v62
	v_mul_f32_e32 v63, v10, v63
	v_mul_f32_e32 v60, v10, v60
	v_mul_f32_e32 v61, v10, v61
	v_mul_f32_e32 v58, v10, v58
	v_mul_f32_e32 v59, v10, v59
	v_mul_f32_e32 v56, v10, v56
	v_mul_f32_e32 v57, v10, v57
	v_mul_f32_e32 v54, v10, v54
	v_mul_f32_e32 v55, v10, v55
	v_mul_f32_e32 v52, v10, v52
	v_mul_f32_e32 v53, v10, v53
	v_mul_f32_e32 v50, v10, v50
	v_mul_f32_e32 v51, v10, v51
	v_mul_f32_e32 v48, v10, v48
	v_mul_f32_e32 v49, v10, v49
	s_branch .Lrs_2

.LBB0_365:
	v_add_f32_e32 v11, 0, v235
	v_add_f32_e32 v11, v236, v11
	v_add_f32_e32 v11, v237, v11
	v_add_f32_e32 v11, v238, v11
	v_add_f32_e32 v11, v239, v11
	v_add_f32_e32 v11, v240, v11
	v_add_f32_e32 v11, v241, v11
	v_add_f32_e32 v11, v242, v11
	v_add_f32_e32 v11, v243, v11
	v_add_f32_e32 v11, v244, v11
	v_add_f32_e32 v11, v245, v11
	v_add_f32_e32 v11, v246, v11
	v_add_f32_e32 v11, v247, v11
	v_add_f32_e32 v11, v248, v11
	v_add_f32_e32 v11, v249, v11
	v_add_f32_e32 v160, v250, v11
	s_mov_b64 vcc, s[98:99]
	s_cbranch_vccz .Lrse_4
	v_sub_f32_e32 v10, v233, v234
	v_exp_f32_e32 v10, v10
	s_nop 0
	v_fmac_f32_e32 v160, v232, v10
	v_mul_f32_e32 v78, v10, v78
	v_mul_f32_e32 v79, v10, v79
	v_mul_f32_e32 v76, v10, v76
	v_mul_f32_e32 v77, v10, v77
	v_mul_f32_e32 v74, v10, v74
	v_mul_f32_e32 v75, v10, v75
	v_mul_f32_e32 v72, v10, v72
	v_mul_f32_e32 v73, v10, v73
	v_mul_f32_e32 v70, v10, v70
	v_mul_f32_e32 v71, v10, v71
	v_mul_f32_e32 v68, v10, v68
	v_mul_f32_e32 v69, v10, v69
	v_mul_f32_e32 v66, v10, v66
	v_mul_f32_e32 v67, v10, v67
	v_mul_f32_e32 v64, v10, v64
	v_mul_f32_e32 v65, v10, v65
	v_mul_f32_e32 v62, v10, v62
	v_mul_f32_e32 v63, v10, v63
	v_mul_f32_e32 v60, v10, v60
	v_mul_f32_e32 v61, v10, v61
	v_mul_f32_e32 v58, v10, v58
	v_mul_f32_e32 v59, v10, v59
	v_mul_f32_e32 v56, v10, v56
	v_mul_f32_e32 v57, v10, v57
	v_mul_f32_e32 v54, v10, v54
	v_mul_f32_e32 v55, v10, v55
	v_mul_f32_e32 v52, v10, v52
	v_mul_f32_e32 v53, v10, v53
	v_mul_f32_e32 v50, v10, v50
	v_mul_f32_e32 v51, v10, v51
	v_mul_f32_e32 v48, v10, v48
	v_mul_f32_e32 v49, v10, v49
	s_branch .Lrs_4

.LBB0_381:
	v_add_f32_e32 v11, 0, v15
	v_add_f32_e32 v11, v233, v11
	v_add_f32_e32 v11, v235, v11
	v_add_f32_e32 v11, v236, v11
	v_add_f32_e32 v11, v237, v11
	v_add_f32_e32 v11, v238, v11
	v_add_f32_e32 v11, v239, v11
	v_add_f32_e32 v11, v240, v11
	v_add_f32_e32 v11, v241, v11
	v_add_f32_e32 v11, v242, v11
	v_add_f32_e32 v11, v243, v11
	v_add_f32_e32 v11, v244, v11
	v_add_f32_e32 v11, v245, v11
	v_add_f32_e32 v11, v246, v11
	v_add_f32_e32 v11, v247, v11
	v_add_f32_e32 v233, v248, v11
	s_mov_b64 vcc, s[98:99]
	s_cbranch_vccz .Lrse_6
	v_sub_f32_e32 v10, v234, v231
	v_exp_f32_e32 v10, v10
	s_nop 0
	v_fmac_f32_e32 v233, v232, v10
	v_mul_f32_e32 v78, v10, v78
	v_mul_f32_e32 v79, v10, v79
	v_mul_f32_e32 v76, v10, v76
	v_mul_f32_e32 v77, v10, v77
	v_mul_f32_e32 v74, v10, v74
	v_mul_f32_e32 v75, v10, v75
	v_mul_f32_e32 v72, v10, v72
	v_mul_f32_e32 v73, v10, v73
	v_mul_f32_e32 v70, v10, v70
	v_mul_f32_e32 v71, v10, v71
	v_mul_f32_e32 v68, v10, v68
	v_mul_f32_e32 v69, v10, v69
	v_mul_f32_e32 v66, v10, v66
	v_mul_f32_e32 v67, v10, v67
	v_mul_f32_e32 v64, v10, v64
	v_mul_f32_e32 v65, v10, v65
	v_mul_f32_e32 v62, v10, v62
	v_mul_f32_e32 v63, v10, v63
	v_mul_f32_e32 v60, v10, v60
	v_mul_f32_e32 v61, v10, v61
	v_mul_f32_e32 v58, v10, v58
	v_mul_f32_e32 v59, v10, v59
	v_mul_f32_e32 v56, v10, v56
	v_mul_f32_e32 v57, v10, v57
	v_mul_f32_e32 v54, v10, v54
	v_mul_f32_e32 v55, v10, v55
	v_mul_f32_e32 v52, v10, v52
	v_mul_f32_e32 v53, v10, v53
	v_mul_f32_e32 v50, v10, v50
	v_mul_f32_e32 v51, v10, v51
	v_mul_f32_e32 v48, v10, v48
	v_mul_f32_e32 v49, v10, v49
	s_branch .Lrs_6
